# norm rows loop: each row's gain/scale/shift loads for column groups 1..3 issued together with group 0 (was nine serial L2 round trips per row)
# speedup vs baseline: 1.0043x; 1.0043x over previous
.LBB0_180:
	v_readlane_b32 s0, v253, 39
	s_movk_i32 s3, 0x4000
	v_add_u32_e32 v0, 0xffffc000, v50
	v_mov_b32_e32 v34, s0
	v_readlane_b32 s0, v253, 37
	v_cmp_gt_i32_e32 vcc, s3, v50
	v_min_i32_e32 v12, 0x4000, v50
	v_mov_b32_e32 v35, s0
	v_readlane_b32 s0, v253, 40
	v_cndmask_b32_e32 v3, 0, v51, vcc
	v_cndmask_b32_e32 v2, v0, v50, vcc
	v_mov_b32_e32 v36, s0
	v_readlane_b32 s0, v253, 38
	v_cndmask_b32_e32 v5, v34, v35, vcc
	v_lshlrev_b64 v[2:3], 12, v[2:3]
	v_mov_b32_e32 v37, s0
	v_cndmask_b32_e32 v4, v36, v37, vcc
	v_lshl_add_u64 v[2:3], v[4:5], 0, v[2:3]
	v_lshlrev_b32_e32 v0, 2, v52
	v_lshl_add_u64 v[2:3], v[2:3], 0, v[0:1]
	global_load_dwordx4 v[30:33], v[2:3], off
	global_load_dwordx4 v[26:29], v[2:3], off offset:1024
	s_waitcnt lgkmcnt(0)
	global_load_dwordx4 v[18:21], v[2:3], off offset:2048
	s_nop 0
	global_load_dwordx4 v[2:5], v[2:3], off offset:3072
	s_nop 0
	global_load_dwordx4 v[80:83], v[54:55], off
	v_lshl_add_u64 v[10:11], s[42:43], 0, v[50:51]
	v_ashrrev_i32_e32 v12, 11, v12
	v_readlane_b32 s0, v253, 41
	v_mov_b64_e32 v[6:7], s[36:37]
	v_lshl_add_u64 v[70:71], s[42:43], 0, v[10:11]
	v_add_u32_e32 v11, s0, v12
	s_movk_i32 s0, 0x3000
	v_mad_i64_i32 v[6:7], s[0:1], v11, s0, v[6:7]
	s_mov_b64 s[0:1], 0x1000
	s_nop 0
	v_lshl_add_u64 v[92:93], v[6:7], 0, s[0:1]
	v_lshl_add_u64 v[12:13], v[92:93], 0, v[0:1]
	global_load_dwordx4 v[84:87], v[12:13], off
	v_lshl_add_u64 v[94:95], v[6:7], 0, v[0:1]
	global_load_dwordx4 v[88:91], v[94:95], off
	v_mov_b32_e32 v65, v1
	v_mov_b32_e32 v67, v1
	v_mov_b32_e32 v69, v1
	global_load_dwordx4 v[98:101], v[54:55], off offset:1024
	v_lshl_add_u64 v[102:103], v[92:93], 0, v[64:65]
	global_load_dwordx4 v[102:105], v[102:103], off
	global_load_dwordx4 v[106:109], v[94:95], off offset:1024
	global_load_dwordx4 v[110:113], v[54:55], off offset:2048
	v_lshl_add_u64 v[114:115], v[92:93], 0, v[66:67]
	global_load_dwordx4 v[114:117], v[114:115], off
	global_load_dwordx4 v[118:121], v[94:95], off offset:2048
	global_load_dwordx4 v[122:125], v[54:55], off offset:3072
	v_lshl_add_u64 v[126:127], v[92:93], 0, v[68:69]
	global_load_dwordx4 v[126:129], v[126:127], off
	global_load_dwordx4 v[130:133], v[94:95], off offset:3072
	v_lshl_add_u64 v[8:9], v[62:63], 0, v[58:59]
	s_mov_b32 s0, 0x133c000
	v_add_co_u32_e32 v72, vcc, s0, v8
	s_movk_i32 s2, 0x4800
	s_nop 0
	v_addc_co_u32_e32 v73, vcc, 0, v9, vcc
	v_cmp_gt_i32_e64 s[0:1], s2, v10
	v_cmp_gt_i32_e32 vcc, s2, v70
	v_mov_b32_e32 v65, v1
	v_cndmask_b32_e64 v38, v50, v10, s[0:1]
	v_ashrrev_i32_e32 v39, 31, v38
	v_add_u32_e32 v40, 0xffffc000, v38
	v_cmp_gt_i32_e64 s[4:5], s3, v38
	s_waitcnt vmcnt(6)
	v_mov_b32_e32 v8, v31
	s_waitcnt vmcnt(5)
	v_mov_b32_e32 v9, v27
	v_mov_b32_e32 v6, v30
	v_mov_b32_e32 v7, v26
	s_waitcnt vmcnt(4)
	v_mov_b32_e32 v14, v19
	s_waitcnt vmcnt(3)
	v_mov_b32_e32 v15, v3
	v_pk_mul_f32 v[8:9], v[8:9], v[8:9]
	v_mov_b32_e32 v10, v32
	v_mov_b32_e32 v11, v28
	v_mov_b32_e32 v12, v18
	v_mov_b32_e32 v13, v2
	v_pk_mul_f32 v[14:15], v[14:15], v[14:15]
	v_pk_fma_f32 v[6:7], v[6:7], v[6:7], v[8:9]
	v_mov_b32_e32 v16, v33
	v_mov_b32_e32 v17, v29
	v_mov_b32_e32 v22, v20
	v_mov_b32_e32 v23, v4
	v_pk_fma_f32 v[8:9], v[12:13], v[12:13], v[14:15]
	v_pk_fma_f32 v[6:7], v[10:11], v[10:11], v[6:7]
	v_mov_b32_e32 v24, v21
	v_mov_b32_e32 v25, v5
	v_pk_fma_f32 v[8:9], v[22:23], v[22:23], v[8:9]
	v_pk_fma_f32 v[6:7], v[16:17], v[16:17], v[6:7]
	v_pk_fma_f32 v[8:9], v[24:25], v[24:25], v[8:9]
	v_add_f32_e32 v6, v6, v7
	v_add_f32_e32 v6, v6, v8
	v_add_f32_e32 v8, v6, v9
	v_mov_b32_e32 v9, v8
	s_nop 1
	v_permlane32_swap_b32_e32 v8, v9
	v_cndmask_b32_e32 v10, v50, v70, vcc
	v_cndmask_b32_e64 v7, 0, v39, s[4:5]
	v_cndmask_b32_e64 v6, v40, v38, s[4:5]
	v_add_u32_e32 v14, 0xffffc000, v10
	s_waitcnt lgkmcnt(0)
	v_add_f32_e32 v11, v8, v9
	v_mov_b32_e32 v12, v11
	s_nop 1
	v_permlane16_swap_b32_e32 v11, v12
	v_cndmask_b32_e64 v9, v34, v35, s[4:5]
	v_cndmask_b32_e64 v8, v36, v37, s[4:5]
	v_cmp_gt_i32_e64 s[4:5], s3, v10
	v_ashrrev_i32_e32 v13, 31, v10
	s_waitcnt lgkmcnt(0)
	v_add_f32_e32 v15, v11, v12
	s_nop 1
	v_mov_b32_dpp v16, v15 row_ror:8 row_mask:0xf bank_mask:0xf
	v_cndmask_b32_e64 v10, v14, v10, s[4:5]
	v_cndmask_b32_e64 v11, 0, v13, s[4:5]
	v_lshlrev_b64 v[6:7], 12, v[6:7]
	v_lshl_add_u64 v[6:7], v[8:9], 0, v[6:7]
	s_waitcnt lgkmcnt(0)
	v_add_f32_e32 v14, v15, v16
	s_nop 1
	v_mov_b32_dpp v15, v14 row_ror:4 row_mask:0xf bank_mask:0xf
	v_lshlrev_b64 v[8:9], 12, v[10:11]
	v_cndmask_b32_e64 v13, v34, v35, s[4:5]
	v_cndmask_b32_e64 v12, v36, v37, s[4:5]
	v_lshl_add_u64 v[8:9], v[12:13], 0, v[8:9]
	s_waitcnt lgkmcnt(0)
	v_add_f32_e32 v10, v14, v15
	s_nop 1
	v_mov_b32_dpp v11, v10 quad_perm:[2,3,0,1] row_mask:0xf bank_mask:0xf
	v_lshl_add_u64 v[6:7], v[6:7], 0, v[0:1]
	v_lshl_add_u64 v[8:9], v[8:9], 0, v[0:1]
	global_load_dwordx4 v[46:49], v[6:7], off
	global_load_dwordx4 v[42:45], v[6:7], off offset:1024
	global_load_dwordx4 v[38:41], v[6:7], off offset:2048
	global_load_dwordx4 v[34:37], v[6:7], off offset:3072
	global_load_dwordx4 v[22:25], v[8:9], off
	global_load_dwordx4 v[14:17], v[8:9], off offset:1024
	s_waitcnt lgkmcnt(0)
	v_add_f32_e32 v10, v10, v11
	s_nop 1
	v_mov_b32_dpp v11, v10 quad_perm:[1,0,3,2] row_mask:0xf bank_mask:0xf
	s_waitcnt vmcnt(7)
	v_pk_add_f32 v[84:85], v[84:85], 1.0 op_sel_hi:[1,0]
	v_pk_add_f32 v[86:87], v[86:87], 1.0 op_sel_hi:[1,0]
	s_waitcnt lgkmcnt(0)
	v_add_f32_e32 v6, v10, v11
	v_fmamk_f32 v6, v6, 0x3a800000, v196
	v_mul_f32_e32 v7, 0x4b800000, v6
	v_cmp_gt_f32_e64 s[4:5], s33, v6
	s_waitcnt vmcnt(1)
	v_mul_f32_e32 v71, v23, v23
	v_cndmask_b32_e64 v6, v6, v7, s[4:5]
	v_rsq_f32_e32 v67, v6
	global_load_dwordx4 v[10:13], v[8:9], off offset:2048
	s_nop 0
	global_load_dwordx4 v[6:9], v[8:9], off offset:3072
	s_waitcnt vmcnt(2)
	v_mul_f32_e32 v79, v15, v15
	v_fmac_f32_e32 v71, v22, v22
	v_mul_f32_e32 v69, 0x45800000, v67
	v_cndmask_b32_e64 v96, v67, v69, s[4:5]
	v_pk_mul_f32 v[30:31], v[30:31], v[96:97] op_sel_hi:[1,0]
	v_pk_mul_f32 v[32:33], v[32:33], v[96:97] op_sel_hi:[1,0]
	v_pk_mul_f32 v[30:31], v[30:31], v[80:81]
	v_pk_mul_f32 v[32:33], v[32:33], v[82:83]
	v_pk_fma_f32 v[30:31], v[30:31], v[84:85], v[88:89]
	v_pk_fma_f32 v[32:33], v[32:33], v[86:87], v[90:91]
	v_cvt_pk_bf16_f32 v30, v30, v31
	v_cvt_pk_bf16_f32 v31, v32, v33
	global_store_dwordx2 v[72:73], v[30:31], off
	s_nop 0
	v_pk_mul_f32 v[26:27], v[26:27], v[96:97] op_sel_hi:[1,0]
	v_pk_mul_f32 v[28:29], v[28:29], v[96:97] op_sel_hi:[1,0]
	v_mov_b32_e32 v67, v1
	v_pk_mul_f32 v[18:19], v[18:19], v[96:97] op_sel_hi:[1,0]
	v_pk_mul_f32 v[20:21], v[20:21], v[96:97] op_sel_hi:[1,0]
	v_mov_b32_e32 v69, v1
	v_fmac_f32_e32 v79, v14, v14
	v_fmac_f32_e32 v71, v24, v24
	v_fmac_f32_e32 v79, v16, v16
	v_fmac_f32_e32 v71, v25, v25
	v_fmac_f32_e32 v79, v17, v17
	v_pk_mul_f32 v[2:3], v[2:3], v[96:97] op_sel_hi:[1,0]
	v_pk_mul_f32 v[4:5], v[4:5], v[96:97] op_sel_hi:[1,0]
	s_waitcnt vmcnt(2)
	v_pk_mul_f32 v[26:27], v[26:27], v[98:99]
	v_pk_mul_f32 v[28:29], v[28:29], v[100:101]
	s_waitcnt vmcnt(1)
	v_pk_add_f32 v[30:31], v[102:103], 1.0 op_sel_hi:[1,0]
	v_pk_add_f32 v[32:33], v[104:105], 1.0 op_sel_hi:[1,0]
	s_waitcnt vmcnt(0)
	v_pk_fma_f32 v[26:27], v[26:27], v[30:31], v[106:107]
	v_pk_fma_f32 v[28:29], v[28:29], v[32:33], v[108:109]
	v_cvt_pk_bf16_f32 v26, v26, v27
	v_cvt_pk_bf16_f32 v27, v28, v29
	global_store_dwordx2 v[72:73], v[26:27], off offset:512
	s_nop 0
	s_waitcnt vmcnt(2)
	v_pk_mul_f32 v[18:19], v[18:19], v[110:111]
	v_pk_mul_f32 v[20:21], v[20:21], v[112:113]
	s_waitcnt vmcnt(1)
	v_pk_add_f32 v[26:27], v[114:115], 1.0 op_sel_hi:[1,0]
	v_pk_add_f32 v[28:29], v[116:117], 1.0 op_sel_hi:[1,0]
	s_waitcnt vmcnt(0)
	v_pk_fma_f32 v[18:19], v[18:19], v[26:27], v[118:119]
	v_pk_fma_f32 v[20:21], v[20:21], v[28:29], v[120:121]
	v_cvt_pk_bf16_f32 v18, v18, v19
	v_cvt_pk_bf16_f32 v19, v20, v21
	global_store_dwordx2 v[72:73], v[18:19], off offset:1024
	v_mul_f32_e32 v18, v47, v47
	v_mul_f32_e32 v19, v43, v43
	v_mul_f32_e32 v20, v39, v39
	v_fmac_f32_e32 v18, v46, v46
	v_fmac_f32_e32 v19, v42, v42
	v_mul_f32_e32 v84, v11, v11
	v_mul_f32_e32 v21, v35, v35
	v_fmac_f32_e32 v20, v38, v38
	v_mul_f32_e32 v85, v7, v7
	v_fmac_f32_e32 v18, v48, v48
	v_fmac_f32_e32 v19, v44, v44
	v_fmac_f32_e32 v84, v10, v10
	v_fmac_f32_e32 v21, v34, v34
	v_fmac_f32_e32 v20, v40, v40
	v_fmac_f32_e32 v85, v6, v6
	v_fmac_f32_e32 v18, v49, v49
	v_fmac_f32_e32 v19, v45, v45
	v_fmac_f32_e32 v84, v12, v12
	v_fmac_f32_e32 v21, v36, v36
	v_fmac_f32_e32 v20, v41, v41
	v_fmac_f32_e32 v85, v8, v8
	v_add_f32_e32 v18, v18, v19
	v_fmac_f32_e32 v84, v13, v13
	v_add_f32_e32 v19, v71, v79
	v_fmac_f32_e32 v21, v37, v37
	v_fmac_f32_e32 v85, v9, v9
	v_add_f32_e32 v18, v18, v20
	v_add_f32_e32 v19, v19, v84
	v_add_f32_e32 v18, v18, v21
	v_add_f32_e32 v19, v19, v85
	v_mov_b32_e32 v20, v18
	s_nop 1
	v_permlane32_swap_b32_e32 v18, v20
	v_mov_b32_e32 v21, v19
	s_nop 1
	v_permlane32_swap_b32_e32 v19, v21
	s_waitcnt lgkmcnt(1)
	v_add_f32_e32 v18, v18, v20
	s_waitcnt lgkmcnt(0)
	v_add_f32_e32 v19, v19, v21
	v_mov_b32_e32 v20, v18
	s_nop 1
	v_permlane16_swap_b32_e32 v18, v20
	v_mov_b32_e32 v21, v19
	s_nop 1
	v_permlane16_swap_b32_e32 v19, v21
	s_waitcnt lgkmcnt(1)
	v_add_f32_e32 v18, v18, v20
	s_waitcnt lgkmcnt(0)
	v_add_f32_e32 v19, v19, v21
	v_mov_b32_dpp v20, v18 row_ror:8 row_mask:0xf bank_mask:0xf
	s_nop 0
	v_mov_b32_dpp v21, v19 row_ror:8 row_mask:0xf bank_mask:0xf
	s_waitcnt lgkmcnt(1)
	v_add_f32_e32 v18, v18, v20
	s_waitcnt lgkmcnt(0)
	v_add_f32_e32 v19, v19, v21
	v_mov_b32_dpp v20, v18 row_ror:4 row_mask:0xf bank_mask:0xf
	s_nop 0
	v_mov_b32_dpp v21, v19 row_ror:4 row_mask:0xf bank_mask:0xf
	s_waitcnt lgkmcnt(1)
	v_add_f32_e32 v18, v18, v20
	s_waitcnt lgkmcnt(0)
	v_add_f32_e32 v19, v19, v21
	v_mov_b32_dpp v20, v18 quad_perm:[2,3,0,1] row_mask:0xf bank_mask:0xf
	s_nop 0
	v_mov_b32_dpp v21, v19 quad_perm:[2,3,0,1] row_mask:0xf bank_mask:0xf
	s_waitcnt lgkmcnt(1)
	v_add_f32_e32 v20, v18, v20
	s_waitcnt lgkmcnt(0)
	v_add_f32_e32 v18, v19, v21
	v_mov_b32_dpp v21, v20 quad_perm:[1,0,3,2] row_mask:0xf bank_mask:0xf
	s_nop 0
	v_mov_b32_dpp v19, v18 quad_perm:[1,0,3,2] row_mask:0xf bank_mask:0xf
	s_waitcnt vmcnt(2)
	v_pk_mul_f32 v[2:3], v[2:3], v[122:123]
	v_pk_mul_f32 v[4:5], v[4:5], v[124:125]
	s_waitcnt vmcnt(1)
	v_pk_add_f32 v[26:27], v[126:127], 1.0 op_sel_hi:[1,0]
	v_pk_add_f32 v[28:29], v[128:129], 1.0 op_sel_hi:[1,0]
	s_waitcnt vmcnt(0)
	v_pk_fma_f32 v[2:3], v[2:3], v[26:27], v[130:131]
	v_pk_fma_f32 v[4:5], v[4:5], v[28:29], v[132:133]
	v_cvt_pk_bf16_f32 v2, v2, v3
	v_cvt_pk_bf16_f32 v3, v4, v5
	global_store_dwordx2 v[72:73], v[2:3], off offset:1536
	s_and_saveexec_b64 s[12:13], s[0:1]
	s_cbranch_execz .LBB0_182
	v_add_u32_e32 v2, s42, v50
	v_min_i32_e32 v2, 0x4000, v2
	v_ashrrev_i32_e32 v2, 11, v2
	v_readlane_b32 s0, v253, 41
	s_waitcnt lgkmcnt(1)
	v_add_f32_e32 v71, v20, v21
	v_fmamk_f32 v71, v71, 0x3a800000, v196
	v_add_u32_e32 v4, s0, v2
	v_mov_b64_e32 v[2:3], s[36:37]
	s_movk_i32 s0, 0x3000
	v_mad_i64_i32 v[30:31], s[0:1], v4, s0, v[2:3]
	s_mov_b64 s[0:1], 0x1000
	s_nop 0
	v_lshl_add_u64 v[72:73], v[30:31], 0, s[0:1]
	v_lshl_add_u64 v[26:27], v[72:73], 0, v[0:1]
	global_load_dwordx4 v[2:5], v[54:55], off
	v_lshl_add_u64 v[80:81], v[30:31], 0, v[0:1]
	global_load_dwordx4 v[26:29], v[26:27], off
	v_mul_f32_e32 v79, 0x4b800000, v71
	global_load_dwordx4 v[30:33], v[80:81], off
	v_mov_b32_e32 v65, v1
	v_mov_b32_e32 v67, v1
	v_mov_b32_e32 v69, v1
	global_load_dwordx4 v[98:101], v[54:55], off offset:1024
	v_lshl_add_u64 v[102:103], v[72:73], 0, v[64:65]
	global_load_dwordx4 v[102:105], v[102:103], off
	global_load_dwordx4 v[106:109], v[80:81], off offset:1024
	global_load_dwordx4 v[110:113], v[54:55], off offset:2048
	v_lshl_add_u64 v[114:115], v[72:73], 0, v[66:67]
	global_load_dwordx4 v[114:117], v[114:115], off
	global_load_dwordx4 v[118:121], v[80:81], off offset:2048
	global_load_dwordx4 v[122:125], v[54:55], off offset:3072
	v_lshl_add_u64 v[126:127], v[72:73], 0, v[68:69]
	global_load_dwordx4 v[126:129], v[126:127], off
	global_load_dwordx4 v[130:133], v[80:81], off offset:3072
	v_cmp_gt_f32_e64 s[0:1], s33, v71
	v_lshl_add_u64 v[20:21], v[60:61], 0, v[58:59]
	v_cndmask_b32_e64 v71, v71, v79, s[0:1]
	v_rsq_f32_e32 v71, v71
	s_mov_b32 s2, 0x133c000
	v_add_co_u32_e64 v20, s[4:5], s2, v20
	v_mul_f32_e32 v65, 0x45800000, v71
	v_cndmask_b32_e64 v84, v71, v65, s[0:1]
	v_pk_mul_f32 v[46:47], v[46:47], v[84:85] op_sel_hi:[1,0]
	v_pk_mul_f32 v[48:49], v[48:49], v[84:85] op_sel_hi:[1,0]
	v_addc_co_u32_e64 v21, s[4:5], 0, v21, s[4:5]
	v_pk_mul_f32 v[42:43], v[42:43], v[84:85] op_sel_hi:[1,0]
	v_pk_mul_f32 v[44:45], v[44:45], v[84:85] op_sel_hi:[1,0]
	v_pk_mul_f32 v[38:39], v[38:39], v[84:85] op_sel_hi:[1,0]
	v_pk_mul_f32 v[40:41], v[40:41], v[84:85] op_sel_hi:[1,0]
	v_pk_mul_f32 v[34:35], v[34:35], v[84:85] op_sel_hi:[1,0]
	v_pk_mul_f32 v[36:37], v[36:37], v[84:85] op_sel_hi:[1,0]
	s_waitcnt vmcnt(2)
	v_pk_mul_f32 v[2:3], v[46:47], v[2:3]
	v_pk_mul_f32 v[4:5], v[48:49], v[4:5]
	s_waitcnt vmcnt(1)
	v_pk_add_f32 v[26:27], v[26:27], 1.0 op_sel_hi:[1,0]
	v_pk_add_f32 v[28:29], v[28:29], 1.0 op_sel_hi:[1,0]
	s_waitcnt vmcnt(0)
	v_pk_fma_f32 v[2:3], v[2:3], v[26:27], v[30:31]
	v_pk_fma_f32 v[4:5], v[4:5], v[28:29], v[32:33]
	v_cvt_pk_bf16_f32 v2, v2, v3
	v_cvt_pk_bf16_f32 v3, v4, v5
	global_store_dwordx2 v[20:21], v[2:3], off
	s_nop 0
	s_waitcnt vmcnt(2)
	v_pk_mul_f32 v[2:3], v[42:43], v[98:99]
	s_waitcnt vmcnt(1)
	v_pk_add_f32 v[26:27], v[102:103], 1.0 op_sel_hi:[1,0]
	v_pk_mul_f32 v[4:5], v[44:45], v[100:101]
	v_pk_add_f32 v[28:29], v[104:105], 1.0 op_sel_hi:[1,0]
	s_waitcnt vmcnt(0)
	v_pk_fma_f32 v[2:3], v[2:3], v[26:27], v[106:107]
	v_pk_fma_f32 v[4:5], v[4:5], v[28:29], v[108:109]
	v_cvt_pk_bf16_f32 v2, v2, v3
	v_cvt_pk_bf16_f32 v3, v4, v5
	global_store_dwordx2 v[20:21], v[2:3], off offset:512
	s_nop 0
	s_waitcnt vmcnt(2)
	v_pk_mul_f32 v[2:3], v[38:39], v[110:111]
	s_waitcnt vmcnt(1)
	v_pk_add_f32 v[26:27], v[114:115], 1.0 op_sel_hi:[1,0]
	v_pk_mul_f32 v[4:5], v[40:41], v[112:113]
	v_pk_add_f32 v[28:29], v[116:117], 1.0 op_sel_hi:[1,0]
	s_waitcnt vmcnt(0)
	v_pk_fma_f32 v[2:3], v[2:3], v[26:27], v[118:119]
	v_pk_fma_f32 v[4:5], v[4:5], v[28:29], v[120:121]
	v_cvt_pk_bf16_f32 v2, v2, v3
	v_cvt_pk_bf16_f32 v3, v4, v5
	global_store_dwordx2 v[20:21], v[2:3], off offset:1024
	s_nop 0
	s_waitcnt vmcnt(2)
	v_pk_mul_f32 v[2:3], v[34:35], v[122:123]
	s_waitcnt vmcnt(1)
	v_pk_add_f32 v[26:27], v[126:127], 1.0 op_sel_hi:[1,0]
	v_pk_mul_f32 v[4:5], v[36:37], v[124:125]
	v_pk_add_f32 v[28:29], v[128:129], 1.0 op_sel_hi:[1,0]
	s_waitcnt vmcnt(0)
	v_pk_fma_f32 v[2:3], v[2:3], v[26:27], v[130:131]
	v_pk_fma_f32 v[4:5], v[4:5], v[28:29], v[132:133]
	v_cvt_pk_bf16_f32 v2, v2, v3
	v_cvt_pk_bf16_f32 v3, v4, v5
	global_store_dwordx2 v[20:21], v[2:3], off offset:1536
.LBB0_182:
	s_or_b64 exec, exec, s[12:13]
	s_and_saveexec_b64 s[0:1], vcc
	s_cbranch_execz .LBB0_179
	v_readlane_b32 s2, v255, 5
	v_mov_b32_e32 v65, v1
	v_mov_b32_e32 v67, v1
	v_add_u32_e32 v20, s2, v50
	v_min_i32_e32 v2, 0x4000, v20
	v_ashrrev_i32_e32 v2, 11, v2
	v_readlane_b32 s2, v253, 41
	s_waitcnt lgkmcnt(1)
	v_ashrrev_i32_e32 v21, 31, v20
	v_mov_b32_e32 v69, v1
	v_add_u32_e32 v4, s2, v2
	v_mov_b64_e32 v[2:3], s[36:37]
	s_movk_i32 s2, 0x3000
	v_mad_i64_i32 v[30:31], s[2:3], v4, s2, v[2:3]
	s_mov_b64 s[2:3], 0x1000
	s_nop 0
	v_lshl_add_u64 v[34:35], v[30:31], 0, s[2:3]
	v_lshl_add_u64 v[26:27], v[34:35], 0, v[0:1]
	global_load_dwordx4 v[2:5], v[54:55], off
	v_lshl_add_u64 v[36:37], v[30:31], 0, v[0:1]
	global_load_dwordx4 v[26:29], v[26:27], off
	s_waitcnt lgkmcnt(0)
	v_add_f32_e32 v0, v18, v19
	global_load_dwordx4 v[30:33], v[36:37], off
	v_mov_b32_e32 v65, v1
	v_mov_b32_e32 v67, v1
	v_mov_b32_e32 v69, v1
	global_load_dwordx4 v[98:101], v[54:55], off offset:1024
	v_lshl_add_u64 v[102:103], v[34:35], 0, v[64:65]
	global_load_dwordx4 v[102:105], v[102:103], off
	global_load_dwordx4 v[106:109], v[36:37], off offset:1024
	global_load_dwordx4 v[110:113], v[54:55], off offset:2048
	v_lshl_add_u64 v[114:115], v[34:35], 0, v[66:67]
	global_load_dwordx4 v[114:117], v[114:115], off
	global_load_dwordx4 v[118:121], v[36:37], off offset:2048
	global_load_dwordx4 v[122:125], v[54:55], off offset:3072
	v_lshl_add_u64 v[126:127], v[34:35], 0, v[68:69]
	global_load_dwordx4 v[126:129], v[126:127], off
	global_load_dwordx4 v[130:133], v[36:37], off offset:3072
	v_fmamk_f32 v0, v0, 0x3a800000, v196
	v_mul_f32_e32 v18, 0x4b800000, v0
	v_cmp_gt_f32_e32 vcc, s33, v0
	s_nop 1
	v_cndmask_b32_e32 v0, v0, v18, vcc
	v_rsq_f32_e32 v0, v0
	v_lshlrev_b64 v[18:19], 11, v[20:21]
	v_lshl_add_u64 v[38:39], v[56:57], 0, v[18:19]
	v_mul_f32_e32 v20, 0x45800000, v0
	v_cndmask_b32_e32 v0, v0, v20, vcc
	v_pk_mul_f32 v[20:21], v[22:23], v[0:1] op_sel_hi:[1,0]
	v_pk_mul_f32 v[22:23], v[24:25], v[0:1] op_sel_hi:[1,0]
	v_pk_mul_f32 v[14:15], v[14:15], v[0:1] op_sel_hi:[1,0]
	v_pk_mul_f32 v[16:17], v[16:17], v[0:1] op_sel_hi:[1,0]
	v_pk_mul_f32 v[10:11], v[10:11], v[0:1] op_sel_hi:[1,0]
	v_pk_mul_f32 v[12:13], v[12:13], v[0:1] op_sel_hi:[1,0]
	v_pk_mul_f32 v[6:7], v[6:7], v[0:1] op_sel_hi:[1,0]
	v_pk_mul_f32 v[8:9], v[8:9], v[0:1] op_sel_hi:[1,0]
	s_waitcnt vmcnt(2)
	v_pk_mul_f32 v[2:3], v[20:21], v[2:3]
	v_pk_mul_f32 v[4:5], v[22:23], v[4:5]
	s_waitcnt vmcnt(1)
	v_pk_add_f32 v[20:21], v[26:27], 1.0 op_sel_hi:[1,0]
	v_pk_add_f32 v[22:23], v[28:29], 1.0 op_sel_hi:[1,0]
	s_waitcnt vmcnt(0)
	v_pk_fma_f32 v[2:3], v[2:3], v[20:21], v[30:31]
	v_pk_fma_f32 v[4:5], v[4:5], v[22:23], v[32:33]
	v_cvt_pk_bf16_f32 v2, v2, v3
	v_cvt_pk_bf16_f32 v3, v4, v5
	global_store_dwordx2 v[38:39], v[2:3], off
	s_nop 0
	s_nop 0
	s_waitcnt vmcnt(2)
	v_pk_mul_f32 v[2:3], v[14:15], v[98:99]
	s_waitcnt vmcnt(1)
	v_pk_add_f32 v[14:15], v[102:103], 1.0 op_sel_hi:[1,0]
	v_pk_mul_f32 v[4:5], v[16:17], v[100:101]
	v_pk_add_f32 v[16:17], v[104:105], 1.0 op_sel_hi:[1,0]
	s_waitcnt vmcnt(0)
	v_pk_fma_f32 v[2:3], v[2:3], v[14:15], v[106:107]
	v_pk_fma_f32 v[4:5], v[4:5], v[16:17], v[108:109]
	v_cvt_pk_bf16_f32 v2, v2, v3
	v_cvt_pk_bf16_f32 v3, v4, v5
	global_store_dwordx2 v[38:39], v[2:3], off offset:512
	s_nop 0
	s_waitcnt vmcnt(2)
	v_pk_mul_f32 v[2:3], v[10:11], v[110:111]
	s_waitcnt vmcnt(1)
	v_pk_add_f32 v[10:11], v[114:115], 1.0 op_sel_hi:[1,0]
	v_pk_mul_f32 v[4:5], v[12:13], v[112:113]
	v_pk_add_f32 v[12:13], v[116:117], 1.0 op_sel_hi:[1,0]
	s_waitcnt vmcnt(0)
	v_pk_fma_f32 v[2:3], v[2:3], v[10:11], v[118:119]
	v_pk_fma_f32 v[4:5], v[4:5], v[12:13], v[120:121]
	v_cvt_pk_bf16_f32 v2, v2, v3
	v_cvt_pk_bf16_f32 v3, v4, v5
	global_store_dwordx2 v[38:39], v[2:3], off offset:1024
	s_nop 0
	s_waitcnt vmcnt(2)
	v_pk_mul_f32 v[2:3], v[6:7], v[122:123]
	s_waitcnt vmcnt(1)
	v_pk_add_f32 v[6:7], v[126:127], 1.0 op_sel_hi:[1,0]
	v_pk_mul_f32 v[4:5], v[8:9], v[124:125]
	v_pk_add_f32 v[8:9], v[128:129], 1.0 op_sel_hi:[1,0]
	s_waitcnt vmcnt(0)
	v_pk_fma_f32 v[2:3], v[2:3], v[6:7], v[130:131]
	v_pk_fma_f32 v[4:5], v[4:5], v[8:9], v[132:133]
	v_cvt_pk_bf16_f32 v2, v2, v3
	v_cvt_pk_bf16_f32 v3, v4, v5
	global_store_dwordx2 v[38:39], v[2:3], off offset:1536
	s_branch .LBB0_179
